# MLA item prologue: Q-tile LDS writes deferred behind the rope-slice loads so both load groups are in flight together
# baseline (speedup 1.0000x reference)
; #define LAS __attribute__((address_space(3)))
; __device__ __forceinline__ u32x4 pack8(const float* f) { u32x4 o; o.x = pk2(f[0], f[1]); o.y = pk2(f[2], f[3]); o.z = pk2(f[4], f[5]); o.w = pk2(f[6], f[7]); return o; }
; template <bool MLA>
; __device__ __forceinline__ void attn_phase(const Args& a, LAS unsigned char* lds) {
;     ...
;             for (int idx = tid; idx < 256 * 8; idx += NTHREADS) { const int lr = idx >> 3, ch = idx & 7; const int rr = lr < nq ? lr : 0;
;                 *(LAS u32x4*)(Qs + lr * QST + ch * 8) = *(const u32x4*)(Qg + (qrow0 + rr) * 1536 + h * 96 + ch * 8); }
;             { const int lr = tid >> 1, ch = tid & 1; const int rr = lr < nq ? lr : 0;
;                 const bf16_t* src = Qg + (qrow0 + rr) * 1536 + h * 96 + 64 + ch * 8;
;                 float x1[8], x2[8], o1[8], o2[8]; unpack8(*(const u32x4*)src, x1); unpack8(*(const u32x4*)(src + 16), x2);
;                 const int pos = (samp ? 1024 : p4 * 256) + rr;
;                 const f32x2* cs = rope + pos * 16 + ch * 8;
; #pragma unroll
;                 for (int k = 0; k < 8; ++k) { const f32x2 c = cs[k]; o1[k] = x1[k] * c.x - x2[k] * c.y; o2[k] = x1[k] * c.y + x2[k] * c.x; }
;                 *(LAS u32x4*)(Qs + lr * QST + 64 + ch * 8) = pack8(o1); *(LAS u32x4*)(Qs + lr * QST + 80 + ch * 8) = pack8(o2); }
.LBB0_449:
	s_or_b64 exec, exec, s[0:1]
	v_cmp_gt_i32_e32 vcc, s62, v156
	v_readlane_b32 s2, v253, 50
	v_readlane_b32 s0, v253, 20
	v_cndmask_b32_e32 v2, 0, v156, vcc
	v_ashrrev_i32_e32 v3, 31, v2
	v_readlane_b32 s3, v253, 51
	v_readlane_b32 s1, v253, 21
	v_mov_b32_e32 v127, v1
	s_waitcnt lgkmcnt(0)
	v_lshl_add_u64 v[28:29], s[2:3], 0, v[2:3]
	v_mov_b64_e32 v[32:33], s[0:1]
	s_movk_i32 s2, 0xc00
	v_mad_u64_u32 v[32:33], s[0:1], v28, s2, v[32:33]
	v_mad_i32_i24 v33, v29, s2, v33
	s_lshl_b32 s0, s8, 1
	s_mov_b32 s1, s3
	v_add_lshl_u32 v2, v2, s7, 4
	v_lshl_add_u64 v[28:29], v[32:33], 0, s[0:1]
	v_ashrrev_i32_e32 v3, 31, v2
	v_lshl_add_u64 v[28:29], v[28:29], 0, v[126:127]
	v_lshl_add_u64 v[2:3], v[2:3], 3, v[90:91]
	global_load_dwordx4 v[32:35], v[28:29], off offset:128
	global_load_dwordx4 v[36:39], v[28:29], off offset:160
	global_load_dwordx4 v[40:43], v[2:3], off offset:48
	global_load_dwordx4 v[44:47], v[2:3], off offset:32
	global_load_dwordx4 v[48:51], v[2:3], off offset:16
	global_load_dwordx4 v[52:55], v[2:3], off
	v_mov_b32_e32 v31, 0
	s_and_b64 s[0:1], s[38:39], s[34:35]
	s_xor_b64 s[0:1], s[0:1], -1
	v_mov_b32_e32 v30, v31
	s_waitcnt vmcnt(5)
	v_lshlrev_b32_e32 v2, 16, v32
	s_waitcnt vmcnt(4)
	v_lshlrev_b32_e32 v28, 16, v36
	v_and_b32_e32 v29, 0xffff0000, v36
	s_waitcnt vmcnt(0)
	ds_write_b128 v232, v[216:219]
	ds_write_b128 v233, v[220:223]
	ds_write_b128 v239, v[224:227]
	ds_write_b128 v240, v[228:231]
	v_mov_b32_e32 v56, v52
	v_mov_b32_e32 v57, v54
	v_mov_b32_e32 v54, v53
	v_and_b32_e32 v3, 0xffff0000, v32
	v_pk_mul_f32 v[52:53], v[54:55], v[28:29]
	v_pk_mul_f32 v[28:29], v[56:57], v[28:29]
	v_pk_fma_f32 v[52:53], v[56:57], v[2:3], v[52:53] neg_lo:[0,0,1] neg_hi:[0,0,1]
	v_pk_fma_f32 v[2:3], v[54:55], v[2:3], v[28:29]
	v_lshlrev_b32_e32 v28, 16, v33
	v_and_b32_e32 v29, 0xffff0000, v33
	v_lshlrev_b32_e32 v32, 16, v37
	v_and_b32_e32 v33, 0xffff0000, v37
	v_mov_b32_e32 v36, v48
	v_mov_b32_e32 v37, v50
	v_mov_b32_e32 v50, v49
	v_pk_mul_f32 v[48:49], v[50:51], v[32:33]
	v_pk_mul_f32 v[32:33], v[36:37], v[32:33]
	v_pk_fma_f32 v[48:49], v[36:37], v[28:29], v[48:49] neg_lo:[0,0,1] neg_hi:[0,0,1]
	v_pk_fma_f32 v[28:29], v[50:51], v[28:29], v[32:33]
	v_lshlrev_b32_e32 v36, 16, v38
	v_and_b32_e32 v37, 0xffff0000, v38
	v_mov_b32_e32 v50, v44
	v_mov_b32_e32 v51, v46
	v_mov_b32_e32 v46, v45
	v_lshlrev_b32_e32 v32, 16, v34
	v_and_b32_e32 v33, 0xffff0000, v34
	v_pk_mul_f32 v[44:45], v[46:47], v[36:37]
	v_pk_mul_f32 v[36:37], v[50:51], v[36:37]
	v_pk_fma_f32 v[44:45], v[50:51], v[32:33], v[44:45] neg_lo:[0,0,1] neg_hi:[0,0,1]
	v_pk_fma_f32 v[36:37], v[46:47], v[32:33], v[36:37]
	v_lshlrev_b32_e32 v32, 16, v35
	v_and_b32_e32 v33, 0xffff0000, v35
	v_lshlrev_b32_e32 v34, 16, v39
	v_and_b32_e32 v35, 0xffff0000, v39
	v_mov_b32_e32 v39, v42
	v_mov_b32_e32 v42, v41
	v_mov_b32_e32 v38, v40
	v_pk_mul_f32 v[40:41], v[42:43], v[34:35]
	v_pk_mul_f32 v[34:35], v[38:39], v[34:35]
	v_pk_fma_f32 v[40:41], v[38:39], v[32:33], v[40:41] neg_lo:[0,0,1] neg_hi:[0,0,1]
	v_pk_fma_f32 v[38:39], v[42:43], v[32:33], v[34:35]
	v_cvt_pk_bf16_f32 v32, v52, v53
	v_cvt_pk_bf16_f32 v33, v48, v49
	v_cvt_pk_bf16_f32 v34, v44, v45
	v_cvt_pk_bf16_f32 v35, v40, v41
	ds_write_b128 v158, v[32:35] offset:128
	v_cvt_pk_bf16_f32 v32, v2, v3
	v_cvt_pk_bf16_f32 v33, v28, v29
	v_cvt_pk_bf16_f32 v34, v36, v37
	v_cvt_pk_bf16_f32 v35, v38, v39
	v_mov_b32_e32 v29, v31
	v_mov_b32_e32 v28, v31
	ds_write_b128 v158, v[32:35] offset:160
	s_and_saveexec_b64 s[2:3], s[0:1]
	s_cbranch_execz .LBB0_455
	v_lshl_add_u64 v[28:29], s[56:57], 0, v[92:93]
	s_and_saveexec_b64 s[0:1], s[42:43]
	s_xor_b64 s[0:1], exec, s[0:1]
	v_lshlrev_b64 v[2:3], 6, v[28:29]
	s_movk_i32 s4, 0xff80
	v_lshl_add_u64 v[2:3], v[94:95], 0, v[2:3]
	s_mov_b32 s5, -1
	v_lshl_add_u64 v[2:3], v[2:3], 0, s[4:5]
	s_andn2_saveexec_b64 s[0:1], s[0:1]
	s_cbranch_execz .LBB0_454
	v_readlane_b32 s4, v253, 24
	v_readlane_b32 s8, v253, 50
	v_lshlrev_b64 v[2:3], 12, v[28:29]
	v_readlane_b32 s5, v253, 25
	v_readlane_b32 s9, v253, 51
	s_nop 0
	v_lshl_add_u64 v[2:3], s[4:5], 0, v[2:3]
	s_lshl_b32 s4, s64, 8
	s_mov_b32 s5, s9
	v_lshl_add_u64 v[2:3], v[2:3], 0, s[4:5]
	v_lshl_add_u64 v[2:3], v[96:97], 1, v[2:3]
